# m_dc unit loop rotated: row max/bias, V and gate rows of the next unit are loaded one unit ahead into spare VGPRs
# speedup vs baseline: 1.0016x; 1.0016x over previous
; DI unsigned pk2(float lo, float hi) { f32x2 v = {lo, hi}; bf16x2_t b = __builtin_convertvector(v, bf16x2_t); return __builtin_bit_cast(unsigned, b); }
; DI float bflo(unsigned u) { return __uint_as_float(u << 16); }
; DI float bfhi(unsigned u) { return __uint_as_float(u & 0xffff0000u); }
; DI float fexp(float x) { return __builtin_amdgcn_exp2f(x * LOG2E); }
; DI void phase_m_dc(int wv, const ArgP a) {
;     ...
;     for (int u = blockIdx.x; u < 1024; u += gridDim.x) {
;         const int c = u >> 2, h = u & 3; const size_t t0 = (size_t)c * 64;
;         const float emax = ML[c * 4 + h] - BL[c * 4 + h];
;         bf16x8 bfr[4];
;         { const bf16_t* vp = KVT + (size_t)(512 + h * 256 + 32 * w + r32) * S + t0 + 8 * hi; const float* gp = GE + (size_t)h * S + t0 + 8 * hi;
; #pragma unroll
;           for (int ks = 0; ks < 4; ++ks) { const u32x4 v = *(const u32x4*)(vp + 16 * ks); const f32x4 e0 = *(const f32x4*)(gp + 16 * ks), e1 = *(const f32x4*)(gp + 16 * ks + 4);
;               u32x4 o; o.x = pk2(bflo(v.x) * fexp(e0[0] - emax), bfhi(v.x) * fexp(e0[1] - emax)); o.y = pk2(bflo(v.y) * fexp(e0[2] - emax), bfhi(v.y) * fexp(e0[3] - emax));
;               o.z = pk2(bflo(v.z) * fexp(e1[0] - emax), bfhi(v.z) * fexp(e1[1] - emax)); o.w = pk2(bflo(v.w) * fexp(e1[2] - emax), bfhi(v.w) * fexp(e1[3] - emax));
;               bfr[ks] = __builtin_bit_cast(bf16x8, o); } }
;         const bf16_t* kp = KVT + (size_t)(h * 128 + r32) * S + t0 + 8 * hi;
;         bf16_t* op = CST + ((size_t)(c * 4 + h) * 256 + 32 * w + r32) * 128 + 8 * hi;
.LBB0_1460:
	s_or_b64 exec, exec, s[0:1]
	s_cmpk_lt_i32 s80, 0x400
	s_mov_b64 s[0:1], s[82:83]
	s_mov_b32 s2, s50
	s_waitcnt lgkmcnt(0)
	v_mov_b32_e32 v0, v192
	s_barrier
	s_cselect_b64 s[6:7], -1, 0
	s_and_b64 vcc, exec, s[6:7]
	v_lshl_add_u32 v30, s2, 6, v0
	s_nop 0
	v_readfirstlane_b32 s2, v30
	s_cbranch_vccz .LBB0_1465
	s_load_dwordx2 s[4:5], s[0:1], 0xe8
	s_movk_i32 s3, 0xffe0
	v_and_b32_e32 v48, 31, v0
	s_load_dword s18, s[88:89], 0x0
	v_mov_b32_e32 v33, 0
	s_waitcnt lgkmcnt(0)
	s_add_u32 s12, s4, 0x1d00000
	s_addc_u32 s13, s5, 0
	s_add_u32 s14, s4, 0x1d01000
	s_addc_u32 s15, s5, 0
	s_add_u32 s16, s4, 0x1c80000
	s_addc_u32 s17, s5, 0
	s_add_u32 s0, s4, 0xbe0b000
	s_addc_u32 s1, s5, 0
	s_ashr_i32 s2, s2, 1
	v_mov_b32_e32 v1, s2
	s_and_b32 s8, s2, 0xffffffe0
	v_bfi_b32 v1, s3, v1, v0
	v_lshrrev_b32_e32 v0, 2, v0
	v_and_b32_e32 v0, 8, v0
	s_ashr_i32 s2, s8, 31
	v_or_b32_e32 v2, s8, v48
	v_mov_b32_e32 v3, s2
	v_lshlrev_b32_e32 v32, 1, v0
	s_movk_i32 s2, 0x80
	v_ashrrev_i32_e32 v31, 31, v30
	v_lshl_add_u64 v[4:5], s[4:5], 0, v[32:33]
	v_cmp_gt_i32_e32 vcc, s2, v30
	v_lshl_add_u64 v[6:7], v[30:31], 2, s[4:5]
	s_mov_b64 s[2:3], 0x1d03000
	v_lshlrev_b64 v[2:3], 8, v[2:3]
	v_lshl_add_u64 v[34:35], v[6:7], 0, s[2:3]
	v_lshl_add_u64 v[2:3], v[4:5], 0, v[2:3]
	s_mov_b64 s[2:3], 0x3e0b000
	v_add_u32_e32 v49, 0x200, v1
	v_lshl_add_u64 v[36:37], v[2:3], 0, s[2:3]
	v_lshlrev_b32_e32 v38, 1, v0
	v_mov_b32_e32 v39, v33
	v_lshlrev_b32_e32 v31, 2, v0
	s_mov_b32 s19, 0x100000
	s_mov_b32 s20, 0x200000
	s_mov_b32 s21, 0x300000
	s_mov_b32 s2, s80
	s_mov_b32 s92, s2
	s_ashr_i32 s93, s92, 2
	s_and_b32 s94, s92, 3
	s_lshl_b32 s95, s92, 2
	s_add_u32 s96, s14, s95
	s_addc_u32 s97, s15, 0
	s_add_u32 s98, s12, s95
	s_addc_u32 s99, s13, 0
	s_lshl_b32 s84, s93, 7
	s_mov_b32 s85, 0
	s_lshl_b32 s95, s94, 16
	s_add_u32 s86, s16, s95
	s_addc_u32 s87, s17, 0
	s_lshl_b32 s95, s93, 8
	s_add_u32 s86, s86, s95
	s_addc_u32 s87, s87, 0
	v_lshl_add_u32 v248, s94, 8, v49
	v_ashrrev_i32_e32 v249, 31, v248
	v_lshlrev_b64 v[248:249], 15, v[248:249]
	v_lshl_add_u64 v[248:249], s[0:1], 0, v[248:249]
	v_lshl_add_u64 v[248:249], v[248:249], 0, s[84:85]
	v_lshl_add_u64 v[248:249], v[248:249], 0, v[38:39]
	global_load_dword v241, v33, s[96:97]
	global_load_dword v242, v33, s[98:99]
	global_load_dwordx4 v[188:191], v[248:249], off
	global_load_dwordx4 v[200:203], v[248:249], off offset:32
	global_load_dwordx4 v[220:223], v[248:249], off offset:64
	global_load_dwordx4 v[224:227], v[248:249], off offset:96
	global_load_dwordx4 v[204:207], v31, s[86:87]
	global_load_dwordx4 v[208:211], v31, s[86:87] offset:16
	global_load_dwordx4 v[212:215], v31, s[86:87] offset:64
	global_load_dwordx4 v[216:219], v31, s[86:87] offset:80
	global_load_dwordx4 v[228:231], v31, s[86:87] offset:144
	global_load_dwordx4 v[232:235], v31, s[86:87] offset:128
	global_load_dwordx4 v[236:239], v31, s[86:87] offset:208
	global_load_dwordx4 v[244:247], v31, s[86:87] offset:192
	s_waitcnt vmcnt(0)
	s_branch .LBB0_1463
.LBB0_1462:
	s_or_b64 exec, exec, s[4:5]
	s_waitcnt vmcnt(8)
	s_add_i32 s2, s2, s18
	s_cmpk_lt_i32 s2, 0x400
	s_cbranch_scc0 .LBB0_1465
.LBB0_1463:
	s_ashr_i32 s10, s2, 2
	s_ashr_i32 s3, s2, 31
	s_and_b32 s22, s2, 3
	s_ashr_i32 s11, s10, 31
	s_lshl_b64 s[4:5], s[2:3], 2
	s_add_u32 s8, s14, s4
	s_addc_u32 s9, s15, s5
	s_add_u32 s4, s12, s4
	s_addc_u32 s5, s13, s5
	v_mov_b32_e32 v32, v241
	v_mov_b32_e32 v40, v242
	v_lshl_add_u32 v0, s22, 8, v49
	v_ashrrev_i32_e32 v1, 31, v0
	v_lshlrev_b64 v[0:1], 15, v[0:1]
	v_lshl_add_u64 v[0:1], s[0:1], 0, v[0:1]
	s_lshl_b64 s[4:5], s[10:11], 7
	s_lshl_b32 s8, s22, 16
	v_lshl_add_u64 v[0:1], v[0:1], 0, s[4:5]
	s_add_u32 s23, s16, s8
	v_lshl_add_u64 v[12:13], v[0:1], 0, v[38:39]
	s_addc_u32 s24, s17, 0
	s_lshl_b64 s[8:9], s[10:11], 8
	v_mov_b64_e32 v[18:19], v[188:189]
	v_mov_b64_e32 v[20:21], v[190:191]
	v_mov_b64_e32 v[0:1], v[200:201]
	v_mov_b64_e32 v[2:3], v[202:203]
	s_add_u32 s8, s23, s8
	s_addc_u32 s9, s24, s9
	v_mov_b64_e32 v[22:23], v[204:205]
	v_mov_b64_e32 v[24:25], v[206:207]
	v_mov_b64_e32 v[26:27], v[208:209]
	v_mov_b64_e32 v[28:29], v[210:211]
	v_mov_b64_e32 v[52:53], v[212:213]
	v_mov_b64_e32 v[54:55], v[214:215]
	v_mov_b64_e32 v[8:9], v[216:217]
	v_mov_b64_e32 v[10:11], v[218:219]
	v_mov_b64_e32 v[4:5], v[220:221]
	v_mov_b64_e32 v[6:7], v[222:223]
	v_mov_b64_e32 v[14:15], v[224:225]
	v_mov_b64_e32 v[16:17], v[226:227]
	v_mov_b64_e32 v[56:57], v[228:229]
	v_mov_b64_e32 v[58:59], v[230:231]
	v_mov_b64_e32 v[60:61], v[232:233]
	v_mov_b64_e32 v[62:63], v[234:235]
	v_mov_b64_e32 v[64:65], v[236:237]
	v_mov_b64_e32 v[66:67], v[238:239]
	v_mov_b64_e32 v[68:69], v[244:245]
	v_mov_b64_e32 v[70:71], v[246:247]
	s_lshl_b32 s22, s22, 7
	v_or_b32_e32 v116, s22, v48
	v_mov_b32_e32 v117, 0
	v_lshlrev_b32_e32 v116, 15, v116
	v_lshl_add_u64 v[118:119], s[0:1], 0, v[116:117]
	v_lshl_add_u64 v[118:119], v[118:119], 0, s[4:5]
	v_lshl_add_u64 v[120:121], v[118:119], 0, v[38:39]
	global_load_dwordx4 v[100:103], v[120:121], off
	global_load_dwordx4 v[104:107], v[120:121], off offset:32
	global_load_dwordx4 v[108:111], v[120:121], off offset:64
	global_load_dwordx4 v[112:115], v[120:121], off offset:96
	v_add_co_u32_e64 v122, s[26:27], s19, v120
	s_nop 1
	v_addc_co_u32_e64 v123, s[26:27], 0, v121, s[26:27]
	global_load_dwordx4 v[140:143], v[122:123], off
	global_load_dwordx4 v[144:147], v[122:123], off offset:32
	global_load_dwordx4 v[148:151], v[122:123], off offset:64
	global_load_dwordx4 v[152:155], v[122:123], off offset:96
	v_add_co_u32_e64 v122, s[26:27], s20, v120
	s_nop 1
	v_addc_co_u32_e64 v123, s[26:27], 0, v121, s[26:27]
	global_load_dwordx4 v[156:159], v[122:123], off
; DI unsigned pk2(float lo, float hi) { f32x2 v = {lo, hi}; bf16x2_t b = __builtin_convertvector(v, bf16x2_t); return __builtin_bit_cast(unsigned, b); }
; DI float bflo(unsigned u) { return __uint_as_float(u << 16); }
; DI float bfhi(unsigned u) { return __uint_as_float(u & 0xffff0000u); }
; DI float fexp(float x) { return __builtin_amdgcn_exp2f(x * LOG2E); }
; DI void phase_m_dc(int wv, const ArgP a) {
;     ...
;     for (int u = blockIdx.x; u < 1024; u += gridDim.x) {
;         const int c = u >> 2, h = u & 3; const size_t t0 = (size_t)c * 64;
;         const float emax = ML[c * 4 + h] - BL[c * 4 + h];
;         bf16x8 bfr[4];
;         { const bf16_t* vp = KVT + (size_t)(512 + h * 256 + 32 * w + r32) * S + t0 + 8 * hi; const float* gp = GE + (size_t)h * S + t0 + 8 * hi;
; #pragma unroll
;           for (int ks = 0; ks < 4; ++ks) { const u32x4 v = *(const u32x4*)(vp + 16 * ks); const f32x4 e0 = *(const f32x4*)(gp + 16 * ks), e1 = *(const f32x4*)(gp + 16 * ks + 4);
;               u32x4 o; o.x = pk2(bflo(v.x) * fexp(e0[0] - emax), bfhi(v.x) * fexp(e0[1] - emax)); o.y = pk2(bflo(v.y) * fexp(e0[2] - emax), bfhi(v.y) * fexp(e0[3] - emax));
;               o.z = pk2(bflo(v.z) * fexp(e1[0] - emax), bfhi(v.z) * fexp(e1[1] - emax)); o.w = pk2(bflo(v.w) * fexp(e1[2] - emax), bfhi(v.w) * fexp(e1[3] - emax));
;               bfr[ks] = __builtin_bit_cast(bf16x8, o); } }
;         const bf16_t* kp = KVT + (size_t)(h * 128 + r32) * S + t0 + 8 * hi;
	global_load_dwordx4 v[160:163], v[122:123], off offset:32
	global_load_dwordx4 v[164:167], v[122:123], off offset:64
	global_load_dwordx4 v[168:171], v[122:123], off offset:96
	v_add_co_u32_e64 v122, s[26:27], s21, v120
	s_nop 1
	v_addc_co_u32_e64 v123, s[26:27], 0, v121, s[26:27]
	global_load_dwordx4 v[172:175], v[122:123], off
	global_load_dwordx4 v[176:179], v[122:123], off offset:32
	global_load_dwordx4 v[180:183], v[122:123], off offset:64
	global_load_dwordx4 v[184:187], v[122:123], off offset:96
	s_add_i32 s92, s2, s18
	s_cmpk_lt_i32 s92, 0x400
	s_cselect_b32 s92, s92, s2
	s_ashr_i32 s93, s92, 2
	s_and_b32 s94, s92, 3
	s_lshl_b32 s95, s92, 2
	s_add_u32 s96, s14, s95
	s_addc_u32 s97, s15, 0
	s_add_u32 s98, s12, s95
	s_addc_u32 s99, s13, 0
	s_lshl_b32 s84, s93, 7
	s_mov_b32 s85, 0
	s_lshl_b32 s95, s94, 16
	s_add_u32 s86, s16, s95
	s_addc_u32 s87, s17, 0
	s_lshl_b32 s95, s93, 8
	s_add_u32 s86, s86, s95
	s_addc_u32 s87, s87, 0
	v_lshl_add_u32 v248, s94, 8, v49
	v_ashrrev_i32_e32 v249, 31, v248
	v_lshlrev_b64 v[248:249], 15, v[248:249]
	v_lshl_add_u64 v[248:249], s[0:1], 0, v[248:249]
	v_lshl_add_u64 v[248:249], v[248:249], 0, s[84:85]
	v_lshl_add_u64 v[248:249], v[248:249], 0, v[38:39]
	global_load_dword v241, v33, s[96:97]
	global_load_dword v242, v33, s[98:99]
	global_load_dwordx4 v[188:191], v[248:249], off
	global_load_dwordx4 v[200:203], v[248:249], off offset:32
	global_load_dwordx4 v[220:223], v[248:249], off offset:64
	global_load_dwordx4 v[224:227], v[248:249], off offset:96
	global_load_dwordx4 v[204:207], v31, s[86:87]
	global_load_dwordx4 v[208:211], v31, s[86:87] offset:16
	global_load_dwordx4 v[212:215], v31, s[86:87] offset:64
	global_load_dwordx4 v[216:219], v31, s[86:87] offset:80
	global_load_dwordx4 v[228:231], v31, s[86:87] offset:144
	global_load_dwordx4 v[232:235], v31, s[86:87] offset:128
	global_load_dwordx4 v[236:239], v31, s[86:87] offset:208
	global_load_dwordx4 v[244:247], v31, s[86:87] offset:192
	v_sub_f32_e32 v50, v32, v40
	v_sub_f32_e32 v24, v24, v50
	v_sub_f32_e32 v25, v25, v50
	v_sub_f32_e32 v32, v52, v50
	v_sub_f32_e32 v51, v53, v50
	v_sub_f32_e32 v52, v54, v50
	v_sub_f32_e32 v53, v55, v50
	v_sub_f32_e32 v22, v22, v50
	v_sub_f32_e32 v23, v23, v50
	v_mul_f32_e32 v24, 0x3fb8aa3b, v24
	v_mul_f32_e32 v25, 0x3fb8aa3b, v25
	v_mul_f32_e32 v54, 0x3fb8aa3b, v52
	v_mul_f32_e32 v55, 0x3fb8aa3b, v53
	v_mul_f32_e32 v22, 0x3fb8aa3b, v22
	v_mul_f32_e32 v23, 0x3fb8aa3b, v23
	v_exp_f32_e32 v24, v24
	v_exp_f32_e32 v25, v25
	v_exp_f32_e32 v54, v54
	v_exp_f32_e32 v55, v55
	v_exp_f32_e32 v22, v22
	v_exp_f32_e32 v23, v23
	v_lshlrev_b32_e32 v12, 16, v18
	v_and_b32_e32 v13, 0xffff0000, v18
	v_lshlrev_b32_e32 v18, 16, v19
	v_and_b32_e32 v19, 0xffff0000, v19
	v_lshlrev_b32_e32 v72, 16, v0
	v_and_b32_e32 v73, 0xffff0000, v0
	v_lshlrev_b32_e32 v0, 16, v1
	v_and_b32_e32 v1, 0xffff0000, v1
	v_sub_f32_e32 v26, v26, v50
	v_sub_f32_e32 v27, v27, v50
	v_mul_f32_e32 v26, 0x3fb8aa3b, v26
	v_mul_f32_e32 v27, 0x3fb8aa3b, v27
	v_pk_mul_f32 v[18:19], v[24:25], v[18:19]
	v_pk_mul_f32 v[0:1], v[54:55], v[0:1]
	v_mul_f32_e32 v32, 0x3fb8aa3b, v32
	v_mul_f32_e32 v51, 0x3fb8aa3b, v51
	v_exp_f32_e32 v26, v26
	v_exp_f32_e32 v27, v27
	v_pk_mul_f32 v[12:13], v[22:23], v[12:13]
	v_cvt_pk_bf16_f32 v23, v18, v19
	v_cvt_pk_bf16_f32 v19, v0, v1
	v_or_b32_e32 v0, s22, v48
	v_exp_f32_e32 v52, v32
	v_exp_f32_e32 v53, v51
	v_lshlrev_b32_e32 v32, 15, v0
	v_lshl_add_u64 v[0:1], s[0:1], 0, v[32:33]
	v_lshlrev_b32_e32 v40, 16, v20
	v_and_b32_e32 v41, 0xffff0000, v20
	v_lshl_add_u64 v[0:1], v[0:1], 0, s[4:5]
	v_pk_mul_f32 v[24:25], v[26:27], v[40:41]
	v_lshl_add_u64 v[40:41], v[0:1], 0, v[38:39]
	v_pk_mul_f32 v[26:27], v[52:53], v[72:73]
	v_sub_f32_e32 v8, v8, v50
	v_sub_f32_e32 v1, v9, v50
	v_sub_f32_e32 v28, v28, v50
	v_sub_f32_e32 v29, v29, v50
	v_mul_f32_e32 v0, 0x3fb8aa3b, v8
	v_mul_f32_e32 v1, 0x3fb8aa3b, v1
	v_mul_f32_e32 v28, 0x3fb8aa3b, v28
	v_mul_f32_e32 v29, 0x3fb8aa3b, v29
	v_exp_f32_e32 v0, v0
	v_exp_f32_e32 v1, v1
	v_exp_f32_e32 v28, v28
	v_exp_f32_e32 v29, v29
	v_lshlrev_b32_e32 v8, 16, v2
	v_and_b32_e32 v9, 0xffff0000, v2
	v_sub_f32_e32 v2, v10, v50
	v_mul_f32_e32 v2, 0x3fb8aa3b, v2
	v_lshlrev_b32_e32 v20, 16, v21
	v_and_b32_e32 v21, 0xffff0000, v21
	v_pk_mul_f32 v[0:1], v[0:1], v[8:9]
	v_exp_f32_e32 v8, v2
	v_sub_f32_e32 v2, v11, v50
	v_pk_mul_f32 v[20:21], v[28:29], v[20:21]
	v_mul_f32_e32 v2, 0x3fb8aa3b, v2
	v_cvt_pk_bf16_f32 v24, v24, v25
	v_cvt_pk_bf16_f32 v25, v20, v21
	v_exp_f32_e32 v9, v2
	v_cvt_pk_bf16_f32 v20, v0, v1
	v_lshlrev_b32_e32 v0, 16, v3
	v_and_b32_e32 v1, 0xffff0000, v3
	v_sub_f32_e32 v2, v60, v50
	v_sub_f32_e32 v3, v61, v50
	v_mul_f32_e32 v2, 0x3fb8aa3b, v2
	v_mul_f32_e32 v3, 0x3fb8aa3b, v3
	v_exp_f32_e32 v2, v2
	v_exp_f32_e32 v3, v3
	v_pk_mul_f32 v[0:1], v[8:9], v[0:1]
	v_cvt_pk_bf16_f32 v18, v26, v27
	v_cvt_pk_bf16_f32 v21, v0, v1
	v_lshlrev_b32_e32 v0, 16, v4
	v_and_b32_e32 v1, 0xffff0000, v4
	v_pk_mul_f32 v[0:1], v[2:3], v[0:1]
	v_sub_f32_e32 v2, v62, v50
	v_sub_f32_e32 v3, v63, v50
	v_mul_f32_e32 v2, 0x3fb8aa3b, v2
	v_mul_f32_e32 v3, 0x3fb8aa3b, v3
	v_exp_f32_e32 v2, v2
	v_exp_f32_e32 v3, v3
	v_cvt_pk_bf16_f32 v26, v0, v1
	v_lshlrev_b32_e32 v0, 16, v5
	v_and_b32_e32 v1, 0xffff0000, v5
	v_pk_mul_f32 v[0:1], v[2:3], v[0:1]
	v_sub_f32_e32 v2, v56, v50
	v_sub_f32_e32 v3, v57, v50
	v_mul_f32_e32 v2, 0x3fb8aa3b, v2
	v_mul_f32_e32 v3, 0x3fb8aa3b, v3
	v_exp_f32_e32 v2, v2
	v_exp_f32_e32 v3, v3
	v_cvt_pk_bf16_f32 v27, v0, v1
	v_lshlrev_b32_e32 v0, 16, v6
	v_and_b32_e32 v1, 0xffff0000, v6
	v_pk_mul_f32 v[0:1], v[2:3], v[0:1]
	v_sub_f32_e32 v2, v58, v50
	v_sub_f32_e32 v3, v59, v50
	v_mul_f32_e32 v2, 0x3fb8aa3b, v2
	v_mul_f32_e32 v3, 0x3fb8aa3b, v3
	v_exp_f32_e32 v2, v2
	v_exp_f32_e32 v3, v3
	v_cvt_pk_bf16_f32 v28, v0, v1
	v_lshlrev_b32_e32 v0, 16, v7
	v_and_b32_e32 v1, 0xffff0000, v7
	v_pk_mul_f32 v[0:1], v[2:3], v[0:1]
	v_sub_f32_e32 v2, v68, v50
	v_sub_f32_e32 v3, v69, v50
	v_mul_f32_e32 v2, 0x3fb8aa3b, v2
	v_mul_f32_e32 v3, 0x3fb8aa3b, v3
	v_exp_f32_e32 v2, v2
	v_exp_f32_e32 v3, v3
	v_cvt_pk_bf16_f32 v29, v0, v1
	v_lshlrev_b32_e32 v0, 16, v14
	v_and_b32_e32 v1, 0xffff0000, v14
	v_pk_mul_f32 v[0:1], v[2:3], v[0:1]
	v_sub_f32_e32 v2, v70, v50
	v_sub_f32_e32 v3, v71, v50
	v_mul_f32_e32 v2, 0x3fb8aa3b, v2
	v_mul_f32_e32 v3, 0x3fb8aa3b, v3
	v_exp_f32_e32 v2, v2
	v_exp_f32_e32 v3, v3
	v_cvt_pk_bf16_f32 v56, v0, v1
	v_lshlrev_b32_e32 v0, 16, v15
	v_and_b32_e32 v1, 0xffff0000, v15
	v_cvt_pk_bf16_f32 v22, v12, v13
	v_pk_mul_f32 v[0:1], v[2:3], v[0:1]
	v_sub_f32_e32 v32, v64, v50
	v_cvt_pk_bf16_f32 v57, v0, v1
	s_waitcnt vmcnt(29)
; DI unsigned pk2(float lo, float hi) { f32x2 v = {lo, hi}; bf16x2_t b = __builtin_convertvector(v, bf16x2_t); return __builtin_bit_cast(unsigned, b); }
; DI void phase_m_dc(int wv, const ArgP a) {
;     ...
; #pragma unroll
;         for (int rb = 0; rb < 4; ++rb) { f32x16 acc = {};
; #pragma unroll
;             for (int ks = 0; ks < 4; ++ks) { const bf16x8 ka = *(const bf16x8*)(kp + (size_t)(32 * rb) * S + 16 * ks); acc = __builtin_amdgcn_mfma_f32_32x32x16_bf16(ka, bfr[ks], acc, 0, 0, 0); }
; #pragma unroll
;             for (int p = 0; p < 2; ++p) {
;                 const unsigned a0 = pk2(acc[8 * p], acc[8 * p + 1]), a1 = pk2(acc[8 * p + 2], acc[8 * p + 3]), b0 = pk2(acc[8 * p + 4], acc[8 * p + 5]), b1 = pk2(acc[8 * p + 6], acc[8 * p + 7]);
;                 const auto r0 = __builtin_amdgcn_permlane32_swap(a0, b0, false, false), r1 = __builtin_amdgcn_permlane32_swap(a1, b1, false, false);
;                 *(u32x4*)(op + 32 * rb + 16 * p) = (u32x4){r0[0], r1[0], r0[1], r1[1]}; } }
	v_mfma_f32_32x32x16_bf16 v[0:15], v[100:103], v[22:25], 0
	v_mul_f32_e32 v32, 0x3fb8aa3b, v32
	v_exp_f32_e32 v52, v32
	v_sub_f32_e32 v32, v65, v50
	v_mul_f32_e32 v32, 0x3fb8aa3b, v32
	v_exp_f32_e32 v53, v32
	v_lshlrev_b32_e32 v54, 16, v16
	v_and_b32_e32 v55, 0xffff0000, v16
	s_waitcnt vmcnt(28)
	v_mfma_f32_32x32x16_bf16 v[0:15], v[104:107], v[18:21], v[0:15]
	v_sub_f32_e32 v16, v66, v50
	v_mul_f32_e32 v16, 0x3fb8aa3b, v16
	v_mul_f32_e64 v52, v52, v54
	v_mul_f32_e64 v53, v53, v55
	v_exp_f32_e32 v54, v16
	v_sub_f32_e32 v16, v67, v50
	v_mul_f32_e32 v16, 0x3fb8aa3b, v16
	v_exp_f32_e32 v55, v16
	s_waitcnt vmcnt(27)
	v_mfma_f32_32x32x16_bf16 v[0:15], v[108:111], v[26:29], v[0:15]
	v_lshlrev_b32_e32 v16, 16, v17
	v_and_b32_e32 v17, 0xffff0000, v17
	v_mul_f32_e64 v16, v54, v16
	v_mul_f32_e64 v17, v55, v17
	v_cvt_pk_bf16_f32 v58, v52, v53
	v_cvt_pk_bf16_f32 v59, v16, v17
	s_lshl_b64 s[4:5], s[2:3], 16
	v_lshl_add_u64 v[68:69], v[36:37], 0, s[4:5]
	s_waitcnt vmcnt(26)
	v_mfma_f32_32x32x16_bf16 v[0:15], v[112:115], v[56:59], v[0:15]
	v_add_co_u32_e64 v64, s[4:5], s19, v40
	s_nop 1
	v_addc_co_u32_e64 v65, s[4:5], 0, v41, s[4:5]
	v_add_co_u32_e64 v70, s[4:5], s20, v40
	s_nop 6
	v_cvt_pk_bf16_f32 v0, v0, v1
	v_cvt_pk_bf16_f32 v1, v2, v3
	v_cvt_pk_bf16_f32 v2, v4, v5
	v_cvt_pk_bf16_f32 v3, v6, v7
	s_nop 0
	v_permlane32_swap_b32_e32 v0, v2
	v_permlane32_swap_b32_e32 v1, v3
	global_store_dwordx4 v[68:69], v[0:3], off
	v_cvt_pk_bf16_f32 v4, v8, v9
	v_cvt_pk_bf16_f32 v5, v10, v11
	v_cvt_pk_bf16_f32 v6, v12, v13
	v_cvt_pk_bf16_f32 v7, v14, v15
	s_nop 0
	v_permlane32_swap_b32_e32 v4, v6
	v_permlane32_swap_b32_e32 v5, v7
	global_store_dwordx4 v[68:69], v[4:7], off offset:32
	v_addc_co_u32_e64 v71, s[4:5], 0, v41, s[4:5]
	s_waitcnt vmcnt(27)
	v_mfma_f32_32x32x16_bf16 v[2:17], v[140:143], v[22:25], 0
	s_waitcnt vmcnt(26)
	v_mfma_f32_32x32x16_bf16 v[2:17], v[144:147], v[18:21], v[2:17]
	s_waitcnt vmcnt(25)
	v_mfma_f32_32x32x16_bf16 v[2:17], v[148:151], v[26:29], v[2:17]
	s_waitcnt vmcnt(24)
	v_mfma_f32_32x32x16_bf16 v[2:17], v[152:155], v[56:59], v[2:17]
	s_nop 11
	v_cvt_pk_bf16_f32 v0, v2, v3
	v_cvt_pk_bf16_f32 v1, v4, v5
	v_cvt_pk_bf16_f32 v2, v6, v7
	v_cvt_pk_bf16_f32 v3, v8, v9
	s_nop 0
	v_permlane32_swap_b32_e32 v0, v2
	v_permlane32_swap_b32_e32 v1, v3
	global_store_dwordx4 v[68:69], v[0:3], off offset:64
	v_cvt_pk_bf16_f32 v64, v10, v11
	v_cvt_pk_bf16_f32 v65, v12, v13
	v_cvt_pk_bf16_f32 v66, v14, v15
	s_waitcnt vmcnt(24)
	v_mfma_f32_32x32x16_bf16 v[0:15], v[156:159], v[22:25], 0
	v_cvt_pk_bf16_f32 v67, v16, v17
	v_permlane32_swap_b32_e32 v64, v66
	s_nop 0
	v_permlane32_swap_b32_e32 v65, v67
	global_store_dwordx4 v[68:69], v[64:67], off offset:96
	s_waitcnt vmcnt(24)
	v_mfma_f32_32x32x16_bf16 v[0:15], v[160:163], v[18:21], v[0:15]
	v_add_co_u32_e64 v16, s[4:5], s21, v40
	s_nop 1
	v_addc_co_u32_e64 v17, s[4:5], 0, v41, s[4:5]
	s_waitcnt vmcnt(23)
	v_mfma_f32_32x32x16_bf16 v[0:15], v[164:167], v[26:29], v[0:15]
	s_waitcnt vmcnt(22)
	v_mfma_f32_32x32x16_bf16 v[0:15], v[168:171], v[56:59], v[0:15]
	s_nop 11
	v_cvt_pk_bf16_f32 v0, v0, v1
	v_cvt_pk_bf16_f32 v1, v2, v3
	v_cvt_pk_bf16_f32 v2, v4, v5
	v_cvt_pk_bf16_f32 v3, v6, v7
	s_nop 0
	v_permlane32_swap_b32_e32 v0, v2
	v_permlane32_swap_b32_e32 v1, v3
	global_store_dwordx4 v[68:69], v[0:3], off offset:128
	v_cvt_pk_bf16_f32 v4, v8, v9
	v_cvt_pk_bf16_f32 v5, v10, v11
	v_cvt_pk_bf16_f32 v6, v12, v13
	v_cvt_pk_bf16_f32 v7, v14, v15
	s_nop 0
	v_permlane32_swap_b32_e32 v4, v6
	v_permlane32_swap_b32_e32 v5, v7
	global_store_dwordx4 v[68:69], v[4:7], off offset:160
	s_waitcnt vmcnt(23)
	v_mfma_f32_32x32x16_bf16 v[0:15], v[172:175], v[22:25], 0
	s_waitcnt vmcnt(22)
	v_mfma_f32_32x32x16_bf16 v[0:15], v[176:179], v[18:21], v[0:15]
	s_waitcnt vmcnt(21)
	v_mfma_f32_32x32x16_bf16 v[0:15], v[180:183], v[26:29], v[0:15]
	s_waitcnt vmcnt(20)
	v_mfma_f32_32x32x16_bf16 v[0:15], v[184:187], v[56:59], v[0:15]
	s_nop 11
	v_cvt_pk_bf16_f32 v0, v0, v1
	v_cvt_pk_bf16_f32 v1, v2, v3
	v_cvt_pk_bf16_f32 v2, v4, v5
	v_cvt_pk_bf16_f32 v3, v6, v7
	v_cvt_pk_bf16_f32 v4, v8, v9
	v_cvt_pk_bf16_f32 v5, v10, v11
	v_cvt_pk_bf16_f32 v6, v12, v13
	v_cvt_pk_bf16_f32 v7, v14, v15
	v_permlane32_swap_b32_e32 v0, v2
	v_permlane32_swap_b32_e32 v1, v3
	v_permlane32_swap_b32_e32 v4, v6
	v_permlane32_swap_b32_e32 v5, v7
	global_store_dwordx4 v[68:69], v[0:3], off offset:192
	global_store_dwordx4 v[68:69], v[4:7], off offset:224
	s_and_saveexec_b64 s[4:5], vcc
	s_cbranch_execz .LBB0_1462
; DI float bflo(unsigned u) { return __uint_as_float(u << 16); }
; DI float bfhi(unsigned u) { return __uint_as_float(u & 0xffff0000u); }
; DI float fexp(float x) { return __builtin_amdgcn_exp2f(x * LOG2E); }
; DI void phase_m_dc(int wv, const ArgP a) {
;     ...
;         if (tid < 128) { const bf16_t* kr = KVT + (size_t)(h * 128 + tid) * S + t0; const float* gp = GE + (size_t)h * S + t0; float s = 0.f;
; #pragma unroll
;             for (int p = 0; p < 8; ++p) { const u32x4 v = *(const u32x4*)(kr + 8 * p); const f32x4 e0 = *(const f32x4*)(gp + 8 * p), e1 = *(const f32x4*)(gp + 8 * p + 4);
;                 s += bflo(v.x) * fexp(e0[0] - emax) + bfhi(v.x) * fexp(e0[1] - emax) + bflo(v.y) * fexp(e0[2] - emax) + bfhi(v.y) * fexp(e0[3] - emax)
;                    + bflo(v.z) * fexp(e1[0] - emax) + bfhi(v.z) * fexp(e1[1] - emax) + bflo(v.w) * fexp(e1[2] - emax) + bfhi(v.w) * fexp(e1[3] - emax); }
	global_load_dwordx4 v[10:13], v33, s[8:9]
	global_load_dwordx4 v[14:17], v33, s[8:9] offset:16
	global_load_dwordx4 v[18:21], v33, s[8:9] offset:32
	global_load_dwordx4 v[22:25], v33, s[8:9] offset:48
	global_load_dwordx4 v[26:29], v33, s[8:9] offset:64
	v_add_u32_e32 v0, s22, v30
	v_ashrrev_i32_e32 v1, 31, v0
	v_lshlrev_b64 v[0:1], 15, v[0:1]
	s_lshl_b64 s[10:11], s[10:11], 6
	v_lshl_add_u64 v[0:1], s[0:1], 0, v[0:1]
	v_lshl_add_u64 v[8:9], s[10:11], 1, v[0:1]
	global_load_dwordx4 v[52:55], v[8:9], off offset:16
	global_load_dwordx4 v[56:59], v[8:9], off
	global_load_dwordx4 v[60:63], v33, s[8:9] offset:80
	global_load_dwordx4 v[64:67], v33, s[8:9] offset:112
	global_load_dwordx4 v[68:71], v33, s[8:9] offset:96
	global_load_dwordx4 v[0:3], v[8:9], off offset:32
	global_load_dwordx4 v[4:7], v[8:9], off offset:48
	s_waitcnt vmcnt(11)
	v_sub_f32_e32 v11, v11, v50
	v_sub_f32_e32 v13, v13, v50
	s_waitcnt vmcnt(9)
	v_sub_f32_e32 v19, v19, v50
	v_sub_f32_e32 v10, v10, v50
	v_sub_f32_e32 v12, v12, v50
	v_sub_f32_e32 v16, v16, v50
	v_sub_f32_e32 v18, v18, v50
	v_mul_f32_e32 v11, 0x3fb8aa3b, v11
	v_mul_f32_e32 v13, 0x3fb8aa3b, v13
	v_mul_f32_e32 v19, 0x3fb8aa3b, v19
	v_sub_f32_e32 v15, v15, v50
	v_sub_f32_e32 v20, v20, v50
	v_mul_f32_e32 v10, 0x3fb8aa3b, v10
	v_mul_f32_e32 v32, 0x3fb8aa3b, v12
	v_mul_f32_e32 v41, 0x3fb8aa3b, v16
	v_mul_f32_e32 v51, 0x3fb8aa3b, v18
	v_exp_f32_e32 v12, v11
	v_exp_f32_e32 v16, v13
	v_exp_f32_e32 v13, v19
	v_sub_f32_e32 v14, v14, v50
	v_sub_f32_e32 v17, v17, v50
	v_sub_f32_e32 v21, v21, v50
	s_waitcnt vmcnt(8)
	v_sub_f32_e32 v23, v23, v50
	v_sub_f32_e32 v24, v24, v50
	v_mul_f32_e32 v15, 0x3fb8aa3b, v15
	v_mul_f32_e32 v72, 0x3fb8aa3b, v20
	v_exp_f32_e32 v10, v10
	v_exp_f32_e32 v11, v51
	v_sub_f32_e32 v22, v22, v50
	v_mul_f32_e32 v40, 0x3fb8aa3b, v14
	v_mul_f32_e32 v17, 0x3fb8aa3b, v17
	v_mul_f32_e32 v21, 0x3fb8aa3b, v21
	v_mul_f32_e32 v23, 0x3fb8aa3b, v23
	v_mul_f32_e32 v74, 0x3fb8aa3b, v24
	v_exp_f32_e32 v14, v32
	v_exp_f32_e32 v20, v15
	v_exp_f32_e32 v15, v72
	v_mul_f32_e32 v73, 0x3fb8aa3b, v22
	v_exp_f32_e32 v24, v17
	v_exp_f32_e32 v17, v21
	v_exp_f32_e32 v21, v23
	v_exp_f32_e32 v23, v74
	s_waitcnt vmcnt(6)
	v_and_b32_e32 v75, 0xffff0000, v52
	s_waitcnt vmcnt(5)
	v_and_b32_e32 v74, 0xffff0000, v56
	v_exp_f32_e32 v18, v40
	v_exp_f32_e32 v19, v73
	v_lshlrev_b32_e32 v73, 16, v52
	v_lshlrev_b32_e32 v72, 16, v56
	v_pk_mul_f32 v[12:13], v[12:13], v[74:75]
	v_sub_f32_e32 v25, v25, v50
	v_lshlrev_b32_e32 v77, 16, v53
	v_lshlrev_b32_e32 v76, 16, v57
	v_pk_fma_f32 v[10:11], v[10:11], v[72:73], v[12:13]
	v_mul_f32_e32 v25, 0x3fb8aa3b, v25
	v_exp_f32_e32 v22, v41
	v_and_b32_e32 v53, 0xffff0000, v53
	v_and_b32_e32 v52, 0xffff0000, v57
	v_pk_fma_f32 v[10:11], v[14:15], v[76:77], v[10:11]
	v_exp_f32_e32 v25, v25
	v_lshlrev_b32_e32 v57, 16, v54
	v_lshlrev_b32_e32 v56, 16, v58
	v_pk_fma_f32 v[10:11], v[16:17], v[52:53], v[10:11]
	v_and_b32_e32 v79, 0xffff0000, v54
	v_and_b32_e32 v78, 0xffff0000, v58
	v_pk_fma_f32 v[10:11], v[18:19], v[56:57], v[10:11]
	v_lshlrev_b32_e32 v81, 16, v55
	v_lshlrev_b32_e32 v80, 16, v59
	v_pk_fma_f32 v[10:11], v[20:21], v[78:79], v[10:11]
	v_and_b32_e32 v55, 0xffff0000, v55
	v_and_b32_e32 v54, 0xffff0000, v59
	v_pk_fma_f32 v[10:11], v[22:23], v[80:81], v[10:11]
	v_sub_f32_e32 v18, v27, v50
	v_pk_fma_f32 v[10:11], v[24:25], v[54:55], v[10:11]
	v_mul_f32_e32 v18, 0x3fb8aa3b, v18
	v_add_f32_e32 v10, 0, v10
	v_add_f32_e32 v32, v10, v11
	global_load_dwordx4 v[10:13], v33, s[8:9] offset:144
	global_load_dwordx4 v[14:17], v33, s[8:9] offset:128
	v_exp_f32_e32 v56, v18
	v_sub_f32_e32 v18, v28, v50
	v_mul_f32_e32 v18, 0x3fb8aa3b, v18
	v_exp_f32_e32 v58, v18
	v_sub_f32_e32 v18, v29, v50
	v_mul_f32_e32 v18, 0x3fb8aa3b, v18
	v_sub_f32_e32 v26, v26, v50
	v_exp_f32_e32 v72, v18
	s_waitcnt vmcnt(6)
	v_sub_f32_e32 v18, v60, v50
	v_mul_f32_e32 v26, 0x3fb8aa3b, v26
	v_mul_f32_e32 v18, 0x3fb8aa3b, v18
	v_exp_f32_e32 v40, v26
	v_exp_f32_e32 v60, v18
	v_sub_f32_e32 v18, v61, v50
	s_waitcnt vmcnt(4)
	v_sub_f32_e32 v26, v69, v50
	v_mul_f32_e32 v18, 0x3fb8aa3b, v18
	v_mul_f32_e32 v26, 0x3fb8aa3b, v26
	v_exp_f32_e32 v74, v18
	v_sub_f32_e32 v18, v62, v50
	v_exp_f32_e32 v57, v26
	v_sub_f32_e32 v26, v70, v50
	v_mul_f32_e32 v18, 0x3fb8aa3b, v18
	v_mul_f32_e32 v26, 0x3fb8aa3b, v26
	v_exp_f32_e32 v62, v18
	v_sub_f32_e32 v18, v63, v50
	v_exp_f32_e32 v59, v26
	v_sub_f32_e32 v26, v71, v50
	v_mul_f32_e32 v18, 0x3fb8aa3b, v18
	v_mul_f32_e32 v26, 0x3fb8aa3b, v26
	v_exp_f32_e32 v76, v18
	v_sub_f32_e32 v18, v68, v50
	v_exp_f32_e32 v73, v26
	v_sub_f32_e32 v26, v64, v50
	v_mul_f32_e32 v18, 0x3fb8aa3b, v18
	v_mul_f32_e32 v26, 0x3fb8aa3b, v26
	v_exp_f32_e32 v41, v18
	global_load_dwordx4 v[18:21], v33, s[8:9] offset:176
	global_load_dwordx4 v[22:25], v33, s[8:9] offset:160
	v_exp_f32_e32 v61, v26
	v_sub_f32_e32 v26, v65, v50
	v_mul_f32_e32 v26, 0x3fb8aa3b, v26
	v_exp_f32_e32 v75, v26
	v_sub_f32_e32 v26, v66, v50
	v_mul_f32_e32 v26, 0x3fb8aa3b, v26
	v_exp_f32_e32 v63, v26
	v_sub_f32_e32 v26, v67, v50
	s_waitcnt vmcnt(4)
; DI float bflo(unsigned u) { return __uint_as_float(u << 16); }
; DI float bfhi(unsigned u) { return __uint_as_float(u & 0xffff0000u); }
; DI float fexp(float x) { return __builtin_amdgcn_exp2f(x * LOG2E); }
; DI void phase_m_dc(int wv, const ArgP a) {
;     ...
;         if (tid < 128) { const bf16_t* kr = KVT + (size_t)(h * 128 + tid) * S + t0; const float* gp = GE + (size_t)h * S + t0; float s = 0.f;
; #pragma unroll
;             for (int p = 0; p < 8; ++p) { const u32x4 v = *(const u32x4*)(kr + 8 * p); const f32x4 e0 = *(const f32x4*)(gp + 8 * p), e1 = *(const f32x4*)(gp + 8 * p + 4);
;                 s += bflo(v.x) * fexp(e0[0] - emax) + bfhi(v.x) * fexp(e0[1] - emax) + bflo(v.y) * fexp(e0[2] - emax) + bfhi(v.y) * fexp(e0[3] - emax)
;                    + bflo(v.z) * fexp(e1[0] - emax) + bfhi(v.z) * fexp(e1[1] - emax) + bflo(v.w) * fexp(e1[2] - emax) + bfhi(v.w) * fexp(e1[3] - emax); }
;             NST[(size_t)(c * 4 + h) * 128 + tid] = s; }
	v_and_b32_e32 v67, 0xffff0000, v4
	v_and_b32_e32 v66, 0xffff0000, v0
	v_lshlrev_b32_e32 v65, 16, v4
	v_lshlrev_b32_e32 v64, 16, v0
	v_pk_mul_f32 v[56:57], v[56:57], v[66:67]
	v_mul_f32_e32 v26, 0x3fb8aa3b, v26
	v_pk_fma_f32 v[40:41], v[40:41], v[64:65], v[56:57]
	v_lshlrev_b32_e32 v57, 16, v5
	v_lshlrev_b32_e32 v56, 16, v1
	v_pk_fma_f32 v[40:41], v[58:59], v[56:57], v[40:41]
	v_and_b32_e32 v5, 0xffff0000, v5
	v_and_b32_e32 v4, 0xffff0000, v1
	v_exp_f32_e32 v77, v26
	v_pk_fma_f32 v[0:1], v[72:73], v[4:5], v[40:41]
	v_lshlrev_b32_e32 v5, 16, v6
	v_lshlrev_b32_e32 v4, 16, v2
	v_pk_fma_f32 v[0:1], v[60:61], v[4:5], v[0:1]
	v_and_b32_e32 v5, 0xffff0000, v6
	v_and_b32_e32 v4, 0xffff0000, v2
	v_pk_fma_f32 v[0:1], v[74:75], v[4:5], v[0:1]
	v_lshlrev_b32_e32 v5, 16, v7
	v_lshlrev_b32_e32 v4, 16, v3
	v_pk_fma_f32 v[0:1], v[62:63], v[4:5], v[0:1]
	v_and_b32_e32 v5, 0xffff0000, v7
	v_and_b32_e32 v4, 0xffff0000, v3
	global_load_dwordx4 v[26:29], v[8:9], off offset:64
	global_load_dwordx4 v[52:55], v[8:9], off offset:80
	v_pk_fma_f32 v[40:41], v[76:77], v[4:5], v[0:1]
	global_load_dwordx4 v[0:3], v33, s[8:9] offset:208
	global_load_dwordx4 v[4:7], v33, s[8:9] offset:192
	global_load_dwordx4 v[56:59], v[8:9], off offset:96
	global_load_dwordx4 v[60:63], v[8:9], off offset:112
	v_add_f32_e32 v32, v32, v40
	v_add_f32_e32 v32, v32, v41
	s_waitcnt vmcnt(9)
	v_sub_f32_e32 v13, v13, v50
	s_waitcnt vmcnt(8)
	v_sub_f32_e32 v8, v14, v50
	v_mul_f32_e32 v8, 0x3fb8aa3b, v8
	v_exp_f32_e32 v40, v8
	v_sub_f32_e32 v8, v15, v50
	v_mul_f32_e32 v8, 0x3fb8aa3b, v8
	v_exp_f32_e32 v64, v8
	v_sub_f32_e32 v8, v16, v50
	v_mul_f32_e32 v8, 0x3fb8aa3b, v8
	v_exp_f32_e32 v66, v8
	v_sub_f32_e32 v8, v17, v50
	v_mul_f32_e32 v8, 0x3fb8aa3b, v8
	v_exp_f32_e32 v68, v8
	v_sub_f32_e32 v8, v10, v50
	v_mul_f32_e32 v8, 0x3fb8aa3b, v8
	v_exp_f32_e32 v70, v8
	v_sub_f32_e32 v8, v11, v50
	v_mul_f32_e32 v8, 0x3fb8aa3b, v8
	v_exp_f32_e32 v72, v8
	global_load_dwordx4 v[8:11], v33, s[8:9] offset:240
	global_load_dwordx4 v[14:17], v33, s[8:9] offset:224
	v_mul_f32_e32 v13, 0x3fb8aa3b, v13
	v_exp_f32_e32 v74, v13
	v_sub_f32_e32 v12, v12, v50
	v_mul_f32_e32 v12, 0x3fb8aa3b, v12
	v_exp_f32_e32 v12, v12
	s_lshl_b64 s[8:9], s[2:3], 9
	s_waitcnt vmcnt(8)
	v_sub_f32_e32 v13, v22, v50
	v_mul_f32_e32 v13, 0x3fb8aa3b, v13
	v_exp_f32_e32 v41, v13
	v_sub_f32_e32 v13, v23, v50
	v_mul_f32_e32 v13, 0x3fb8aa3b, v13
	v_exp_f32_e32 v65, v13
	v_sub_f32_e32 v13, v24, v50
	v_mul_f32_e32 v13, 0x3fb8aa3b, v13
	v_exp_f32_e32 v67, v13
	v_sub_f32_e32 v13, v25, v50
	v_mul_f32_e32 v13, 0x3fb8aa3b, v13
	v_exp_f32_e32 v69, v13
	v_sub_f32_e32 v13, v18, v50
	v_mul_f32_e32 v13, 0x3fb8aa3b, v13
	v_exp_f32_e32 v71, v13
	v_sub_f32_e32 v13, v19, v50
	v_mul_f32_e32 v13, 0x3fb8aa3b, v13
	v_sub_f32_e32 v18, v21, v50
	v_exp_f32_e32 v73, v13
	v_sub_f32_e32 v13, v20, v50
	v_mul_f32_e32 v18, 0x3fb8aa3b, v18
	v_exp_f32_e32 v75, v18
	v_mul_f32_e32 v13, 0x3fb8aa3b, v13
	v_exp_f32_e32 v13, v13
	s_waitcnt vmcnt(7)
	v_and_b32_e32 v20, 0xffff0000, v26
	s_waitcnt vmcnt(6)
	v_and_b32_e32 v21, 0xffff0000, v52
	v_lshlrev_b32_e32 v19, 16, v52
	v_lshlrev_b32_e32 v18, 16, v26
	v_pk_mul_f32 v[20:21], v[64:65], v[20:21]
	s_waitcnt vmcnt(5)
	v_sub_f32_e32 v1, v1, v50
	v_pk_fma_f32 v[18:19], v[40:41], v[18:19], v[20:21]
	v_lshlrev_b32_e32 v21, 16, v53
	v_lshlrev_b32_e32 v20, 16, v27
	v_pk_fma_f32 v[18:19], v[66:67], v[20:21], v[18:19]
	v_and_b32_e32 v21, 0xffff0000, v53
	v_and_b32_e32 v20, 0xffff0000, v27
	v_pk_fma_f32 v[18:19], v[68:69], v[20:21], v[18:19]
	v_lshlrev_b32_e32 v21, 16, v54
	v_lshlrev_b32_e32 v20, 16, v28
	v_pk_fma_f32 v[18:19], v[70:71], v[20:21], v[18:19]
	v_and_b32_e32 v21, 0xffff0000, v54
	v_and_b32_e32 v20, 0xffff0000, v28
	v_pk_fma_f32 v[18:19], v[72:73], v[20:21], v[18:19]
	v_lshlrev_b32_e32 v21, 16, v55
	v_lshlrev_b32_e32 v20, 16, v29
	v_pk_fma_f32 v[12:13], v[12:13], v[20:21], v[18:19]
	v_and_b32_e32 v19, 0xffff0000, v55
	v_and_b32_e32 v18, 0xffff0000, v29
	v_mul_f32_e32 v1, 0x3fb8aa3b, v1
	v_pk_fma_f32 v[12:13], v[74:75], v[18:19], v[12:13]
	s_waitcnt vmcnt(4)
	v_sub_f32_e32 v5, v5, v50
	v_exp_f32_e32 v20, v1
	v_sub_f32_e32 v1, v2, v50
	v_add_f32_e32 v12, v32, v12
	v_mul_f32_e32 v5, 0x3fb8aa3b, v5
	v_mul_f32_e32 v1, 0x3fb8aa3b, v1
	v_add_f32_e32 v24, v12, v13
	v_exp_f32_e32 v12, v5
	v_sub_f32_e32 v5, v6, v50
	v_exp_f32_e32 v2, v1
	v_sub_f32_e32 v1, v3, v50
	v_mul_f32_e32 v5, 0x3fb8aa3b, v5
	v_mul_f32_e32 v1, 0x3fb8aa3b, v1
	v_exp_f32_e32 v6, v5
	v_sub_f32_e32 v5, v7, v50
	v_exp_f32_e32 v22, v1
	s_waitcnt vmcnt(0)
	v_sub_f32_e32 v1, v14, v50
	v_mul_f32_e32 v5, 0x3fb8aa3b, v5
	v_mul_f32_e32 v1, 0x3fb8aa3b, v1
	v_exp_f32_e32 v18, v5
	v_exp_f32_e32 v5, v1
	v_sub_f32_e32 v1, v15, v50
	v_mul_f32_e32 v1, 0x3fb8aa3b, v1
	v_exp_f32_e32 v13, v1
	v_sub_f32_e32 v1, v16, v50
	v_sub_f32_e32 v4, v4, v50
	v_mul_f32_e32 v1, 0x3fb8aa3b, v1
	v_mul_f32_e32 v4, 0x3fb8aa3b, v4
	v_exp_f32_e32 v7, v1
	v_sub_f32_e32 v1, v17, v50
	v_exp_f32_e32 v4, v4
	v_mul_f32_e32 v1, 0x3fb8aa3b, v1
	v_sub_f32_e32 v3, v9, v50
	v_sub_f32_e32 v0, v0, v50
	v_exp_f32_e32 v19, v1
	v_sub_f32_e32 v1, v8, v50
	v_mul_f32_e32 v3, 0x3fb8aa3b, v3
	v_sub_f32_e32 v8, v11, v50
	v_mul_f32_e32 v0, 0x3fb8aa3b, v0
	v_mul_f32_e32 v1, 0x3fb8aa3b, v1
	v_exp_f32_e32 v21, v3
	v_sub_f32_e32 v3, v10, v50
	v_mul_f32_e32 v8, 0x3fb8aa3b, v8
	v_and_b32_e32 v11, 0xffff0000, v60
	v_and_b32_e32 v10, 0xffff0000, v56
	v_exp_f32_e32 v0, v0
	v_exp_f32_e32 v1, v1
	v_exp_f32_e32 v23, v8
	v_lshlrev_b32_e32 v9, 16, v60
	v_lshlrev_b32_e32 v8, 16, v56
	v_pk_mul_f32 v[10:11], v[12:13], v[10:11]
	v_mul_f32_e32 v3, 0x3fb8aa3b, v3
	v_pk_fma_f32 v[4:5], v[4:5], v[8:9], v[10:11]
	v_lshlrev_b32_e32 v9, 16, v61
	v_lshlrev_b32_e32 v8, 16, v57
	v_exp_f32_e32 v3, v3
	v_pk_fma_f32 v[4:5], v[6:7], v[8:9], v[4:5]
	v_and_b32_e32 v7, 0xffff0000, v61
	v_and_b32_e32 v6, 0xffff0000, v57
	v_pk_fma_f32 v[4:5], v[18:19], v[6:7], v[4:5]
	v_lshlrev_b32_e32 v7, 16, v62
	v_lshlrev_b32_e32 v6, 16, v58
	v_pk_fma_f32 v[0:1], v[0:1], v[6:7], v[4:5]
	v_and_b32_e32 v5, 0xffff0000, v62
	v_and_b32_e32 v4, 0xffff0000, v58
	v_pk_fma_f32 v[0:1], v[20:21], v[4:5], v[0:1]
	v_lshlrev_b32_e32 v5, 16, v63
	v_lshlrev_b32_e32 v4, 16, v59
	v_pk_fma_f32 v[0:1], v[2:3], v[4:5], v[0:1]
	v_and_b32_e32 v3, 0xffff0000, v63
	v_and_b32_e32 v2, 0xffff0000, v59
	v_pk_fma_f32 v[0:1], v[22:23], v[2:3], v[0:1]
	s_nop 0
	v_add_f32_e32 v0, v24, v0
	v_add_f32_e32 v2, v0, v1
	v_lshl_add_u64 v[0:1], v[34:35], 0, s[8:9]
	global_store_dword v[0:1], v2, off
	s_branch .LBB0_1462
